# row-scale loads (gate|up, w_in, q phases) consumed at the LDS write instead of waited for at once
# speedup vs baseline: 1.0050x; 1.0050x over previous
.LBB11_1155:
	s_mov_b32 s35, s61
	s_lshl_b64 s[0:1], s[34:35], 23
	v_readlane_b32 s9, v245, 7
	s_add_u32 s36, s9, s0
	v_readlane_b32 s0, v245, 8
	s_addc_u32 s37, s0, s1
	v_readlane_b32 s0, v246, 61
	v_readlane_b32 s1, v242, 51
	s_add_u32 s41, s0, s1
	v_readlane_b32 s0, v246, 62
	s_addc_u32 s42, s0, 0
	s_add_u32 s30, s41, 0x10400
	s_addc_u32 s31, s42, 0
	s_mul_i32 s44, s34, 0x20800
	v_readlane_b32 s0, v245, 9
	s_mul_hi_u32 s43, s34, 0x20800
	s_mov_b64 s[94:95], s[34:35]
	s_add_u32 s34, s0, s44
	v_readlane_b32 s0, v245, 10
	s_addc_u32 s35, s0, s43
	s_and_b64 vcc, exec, s[10:11]
	s_mov_b32 s0, s61
	v_writelane_b32 v242, s0, 56
	s_cbranch_vccnz .LBB11_1215
	s_cmp_gt_i32 s7, -1
	s_movk_i32 s9, 0x100
	s_cselect_b64 s[0:1], -1, 0
	v_cmp_gt_i32_e64 s[12:13], s9, v144
	s_and_b64 s[0:1], s[12:13], s[0:1]
	v_mov_b32_e32 v250, 1.0
	s_and_saveexec_b64 s[18:19], s[0:1]
	s_cbranch_execz .LBB11_1158
	v_lshl_add_u32 v2, s7, 8, v144
	v_ashrrev_i32_e32 v3, 31, v2
	v_lshl_add_u64 v[2:3], v[2:3], 2, s[30:31]
	global_load_dword v250, v[2:3], off

.LBB11_1160:
	v_lshl_add_u64 v[10:11], s[28:29], 0, v[0:1]
	v_mov_b32_e32 v135, v1
	v_lshl_add_u64 v[12:13], s[28:29], 0, v[134:135]
	v_mov_b32_e32 v131, v1
	s_add_i32 m0, s46, 0x18000
	v_lshl_add_u64 v[10:11], v[10:11], 0, s[96:97]
	v_lshl_add_u64 v[14:15], s[16:17], 0, v[130:131]
	v_mov_b32_e32 v133, v1
	s_waitcnt vmcnt(2)
	s_barrier
	global_load_lds_dwordx4 v[10:11], off
	v_lshl_add_u64 v[10:11], v[12:13], 0, s[96:97]
	s_add_i32 m0, s46, 0x1a000
	s_add_i32 s58, s46, 0x8000
	s_add_i32 s59, s46, 0xa000
	v_lshl_add_u64 v[16:17], s[16:17], 0, v[132:133]
	global_load_lds_dwordx4 v[10:11], off
	v_lshl_add_u64 v[10:11], v[14:15], 0, s[96:97]
	s_mov_b32 m0, s58
	s_add_u32 s14, s28, 0x40080
	global_load_lds_dwordx4 v[10:11], off
	v_lshl_add_u64 v[10:11], v[16:17], 0, s[96:97]
	s_mov_b32 m0, s59
	s_addc_u32 s15, s29, 0
	global_load_lds_dwordx4 v[10:11], off
	s_add_i32 m0, s46, 0x1c000
	v_lshl_add_u64 v[10:11], s[14:15], 0, v[0:1]
	global_load_lds_dwordx4 v[10:11], off
	v_lshl_add_u64 v[10:11], s[14:15], 0, v[134:135]
	s_add_i32 m0, s46, 0x1e000
	s_nop 0
	global_load_lds_dwordx4 v[10:11], off
	s_waitcnt vmcnt(6)
	s_barrier
	s_and_saveexec_b64 s[14:15], s[12:13]
	s_cbranch_execz .LBB11_1162
	v_fmamk_f32 v4, v250, 0x3a800000, v206
	v_mul_f32_e32 v9, 0x4b800000, v4
	v_cmp_gt_f32_e32 vcc, s77, v4
	s_nop 1
	v_cndmask_b32_e32 v4, v4, v9, vcc
	v_rsq_f32_e32 v4, v4
	v_lshl_add_u32 v9, v144, 2, 0
	v_add_u32_e32 v9, 0x22000, v9
	v_mul_f32_e32 v10, 0x45800000, v4
	v_cndmask_b32_e32 v4, v4, v10, vcc
	ds_write_b32 v9, v4

.LBB11_1175:
	s_cmp_gt_i32 s8, -1
	s_cselect_b64 s[0:1], -1, 0
	s_and_b64 s[0:1], s[12:13], s[0:1]
	v_mov_b32_e32 v150, 1.0
	s_and_saveexec_b64 s[16:17], s[0:1]
	s_cbranch_execz .LBB11_1177
	v_lshl_add_u32 v140, s8, 8, v144
	v_ashrrev_i32_e32 v141, 31, v140
	v_lshl_add_u64 v[140:141], v[140:141], 2, s[30:31]
	global_load_dword v150, v[140:141], off

.LBB11_1211:
	s_waitcnt vmcnt(16)
	v_fmamk_f32 v150, v150, 0x3a800000, v206
	v_mul_f32_e32 v2, 0x4b800000, v150
	v_cmp_gt_f32_e32 vcc, s77, v150
	s_nop 1
	v_cndmask_b32_e32 v2, v150, v2, vcc
	v_rsq_f32_e32 v2, v2
	s_waitcnt lgkmcnt(0)
	v_mul_f32_e32 v3, 0x45800000, v2
	v_cndmask_b32_e32 v2, v2, v3, vcc
	v_lshl_add_u32 v3, s88, 10, v148
	ds_write_b32 v3, v2
	s_or_b64 exec, exec, s[16:17]
	s_andn2_b64 vcc, exec, s[22:23]
	s_mov_b64 s[16:17], -1
	s_cbranch_vccnz .LBB11_1164

.LBB11_1854:
	s_mov_b32 s45, s61
	s_lshl_b64 s[68:69], s[44:45], 21
	v_readlane_b32 s0, v245, 41
	s_add_u32 s34, s0, s68
	v_readlane_b32 s0, v245, 42
	s_addc_u32 s35, s0, s69
	v_readlane_b32 s0, v246, 61
	v_readlane_b32 s1, v242, 51
	s_add_u32 s1, s0, s1
	v_readlane_b32 s0, v246, 62
	s_addc_u32 s0, s0, s58
	v_writelane_b32 v242, s1, 54
	s_add_u32 s30, s1, 0x20800
	v_writelane_b32 v242, s0, 51
	s_addc_u32 s31, s0, 0
	v_readlane_b32 s0, v245, 34
	v_readlane_b32 s1, v245, 35
	v_mov_b32_e32 v144, v199
	s_waitcnt lgkmcnt(0)
	v_cndmask_b32_e64 v0, 0, 1, s[0:1]
	v_cmp_ne_u32_e64 s[90:91], 1, v0
	s_andn2_b64 vcc, exec, s[0:1]
	v_readfirstlane_b32 s8, v144
	s_mov_b64 s[94:95], s[44:45]
	s_cbranch_vccnz .LBB11_1880
	s_movk_i32 s0, 0x100
	v_cmp_gt_i32_e64 s[12:13], s0, v144
	v_readlane_b32 s0, v245, 43
	v_readlane_b32 s1, v245, 44
	s_and_b64 s[0:1], s[0:1], s[12:13]
	v_mov_b32_e32 v250, 1.0
	s_and_saveexec_b64 s[10:11], s[0:1]
	v_readlane_b32 s24, v245, 46
	v_readlane_b32 s25, v245, 47
	s_cbranch_execz .LBB11_1857
	v_readlane_b32 s0, v245, 45
	s_nop 1
	v_add_u32_e32 v2, s0, v144
	v_ashrrev_i32_e32 v3, 31, v2
	v_lshl_add_u64 v[2:3], v[2:3], 2, s[30:31]
	global_load_dword v250, v[2:3], off

.LBB11_1859:
	v_lshl_add_u64 v[10:11], s[10:11], 0, v[0:1]
	v_mov_b32_e32 v135, v1
	v_lshl_add_u64 v[12:13], s[10:11], 0, v[134:135]
	v_mov_b32_e32 v131, v1
	s_add_i32 m0, s7, 0x18000
	v_lshl_add_u64 v[10:11], v[10:11], 0, s[96:97]
	v_lshl_add_u64 v[14:15], s[24:25], 0, v[130:131]
	v_mov_b32_e32 v133, v1
	s_waitcnt vmcnt(2)
	s_barrier
	global_load_lds_dwordx4 v[10:11], off
	v_lshl_add_u64 v[10:11], v[12:13], 0, s[96:97]
	s_add_i32 m0, s7, 0x1a000
	s_add_i32 s37, s7, 0x8000
	s_add_i32 s38, s7, 0xa000
	v_lshl_add_u64 v[16:17], s[24:25], 0, v[132:133]
	global_load_lds_dwordx4 v[10:11], off
	v_lshl_add_u64 v[10:11], v[14:15], 0, s[96:97]
	s_mov_b32 m0, s37
	s_add_u32 s16, s10, 0x40080
	global_load_lds_dwordx4 v[10:11], off
	v_lshl_add_u64 v[10:11], v[16:17], 0, s[96:97]
	s_mov_b32 m0, s38
	s_addc_u32 s17, s11, 0
	global_load_lds_dwordx4 v[10:11], off
	s_add_i32 m0, s7, 0x1c000
	v_lshl_add_u64 v[10:11], s[16:17], 0, v[0:1]
	global_load_lds_dwordx4 v[10:11], off
	v_lshl_add_u64 v[10:11], s[16:17], 0, v[134:135]
	s_add_i32 m0, s7, 0x1e000
	s_nop 0
	global_load_lds_dwordx4 v[10:11], off
	s_waitcnt vmcnt(6)
	s_barrier
	s_and_saveexec_b64 s[16:17], s[12:13]
	s_cbranch_execz .LBB11_1861
	v_fmamk_f32 v3, v250, 0x3a800000, v206
	v_mul_f32_e32 v9, 0x4b800000, v3
	v_cmp_gt_f32_e32 vcc, s77, v3
	s_nop 1
	v_cndmask_b32_e32 v3, v3, v9, vcc
	v_rsq_f32_e32 v3, v3
	v_lshl_add_u32 v9, v144, 2, 0
	v_add_u32_e32 v9, 0x22000, v9
	v_mul_f32_e32 v10, 0x45800000, v3
	v_cndmask_b32_e32 v3, v3, v10, vcc
	ds_write_b32 v9, v3

.LBB11_1872:
	s_cmp_gt_i32 s9, -1
	s_cselect_b64 s[0:1], -1, 0
	s_and_b64 s[0:1], s[12:13], s[0:1]
	v_mov_b32_e32 v150, 1.0
	s_and_saveexec_b64 s[10:11], s[0:1]
	s_mov_b64 s[44:45], s[94:95]
	s_cbranch_execz .LBB11_1874
	v_lshl_add_u32 v140, s9, 8, v144
	v_ashrrev_i32_e32 v141, 31, v140
	v_lshl_add_u64 v[140:141], v[140:141], 2, s[30:31]
	global_load_dword v150, v[140:141], off
.LBB11_1874:
	s_or_b64 exec, exec, s[10:11]
	s_lshl_b32 s0, s39, 10
	v_mov_b32_e32 v140, v145
	v_mov_b32_e32 v142, v147
	s_add_i32 s0, s0, 0
	s_xor_b32 s39, s39, 1
	v_lshl_add_u32 v141, v140, 2, s0
	v_add_u32_e32 v151, 0x22000, v141
	ds_read_b32 v141, v151
	v_readlane_b32 s0, v245, 61
	v_lshl_add_u32 v140, s8, 8, v140
	s_lshl_b32 s0, s0, 8
	s_ashr_i32 s1, s0, 31
	s_waitcnt lgkmcnt(0)
	v_mul_f32_e32 v152, 0x3d800000, v141
	v_ashrrev_i32_e32 v141, 31, v140
	v_lshlrev_b64 v[154:155], 11, v[140:141]
	v_ashrrev_i32_e32 v143, 31, v142
	v_lshl_add_u64 v[154:155], s[78:79], 0, v[154:155]
	s_lshl_b64 s[10:11], s[0:1], 1
	v_lshl_add_u64 v[154:155], v[154:155], 0, s[10:11]
	v_lshlrev_b64 v[142:143], 1, v[142:143]
	v_lshl_add_u64 v[154:155], v[154:155], 0, v[142:143]
	v_pk_mul_f32 v[128:129], v[128:129], v[152:153] op_sel_hi:[1,0]
	v_pk_mul_f32 v[126:127], v[126:127], v[152:153] op_sel_hi:[1,0]
	v_pk_mul_f32 v[156:157], v[124:125], v[152:153] op_sel_hi:[1,0]
	v_pk_mul_f32 v[124:125], v[122:123], v[152:153] op_sel_hi:[1,0]
	v_cvt_pk_bf16_f32 v122, v126, v127
	v_cvt_pk_bf16_f32 v123, v128, v129
	v_pk_mul_f32 v[118:119], v[118:119], v[152:153] op_sel_hi:[1,0]
	v_cvt_pk_bf16_f32 v124, v124, v125
	v_cvt_pk_bf16_f32 v125, v156, v157
	global_store_dwordx4 v[154:155], v[122:125], off
	v_pk_mul_f32 v[120:121], v[120:121], v[152:153] op_sel_hi:[1,0]
	s_nop 0
	v_pk_mul_f32 v[122:123], v[116:117], v[152:153] op_sel_hi:[1,0]
	v_pk_mul_f32 v[116:117], v[114:115], v[152:153] op_sel_hi:[1,0]
	v_cvt_pk_bf16_f32 v114, v118, v119
	v_cvt_pk_bf16_f32 v115, v120, v121
	s_nop 0
	v_cvt_pk_bf16_f32 v116, v116, v117
	v_cvt_pk_bf16_f32 v117, v122, v123
	ds_read_b32 v118, v151 offset:64
	global_store_dwordx4 v[154:155], v[114:117], off offset:256
	s_nop 1
	v_add_u32_e32 v114, 16, v140
	v_ashrrev_i32_e32 v115, 31, v114
	v_lshlrev_b64 v[114:115], 11, v[114:115]
	v_lshl_add_u64 v[114:115], s[78:79], 0, v[114:115]
	s_waitcnt lgkmcnt(0)
	v_mul_f32_e32 v116, 0x3d800000, v118
	v_lshl_add_u64 v[114:115], v[114:115], 0, s[10:11]
	v_lshl_add_u64 v[114:115], v[114:115], 0, v[142:143]
	v_pk_mul_f32 v[112:113], v[112:113], v[116:117] op_sel_hi:[1,0]
	v_pk_mul_f32 v[110:111], v[110:111], v[116:117] op_sel_hi:[1,0]
	v_pk_mul_f32 v[118:119], v[108:109], v[116:117] op_sel_hi:[1,0]
	v_pk_mul_f32 v[108:109], v[106:107], v[116:117] op_sel_hi:[1,0]
	v_cvt_pk_bf16_f32 v106, v110, v111
	v_cvt_pk_bf16_f32 v107, v112, v113
	v_pk_mul_f32 v[102:103], v[102:103], v[116:117] op_sel_hi:[1,0]
	v_cvt_pk_bf16_f32 v108, v108, v109
	v_cvt_pk_bf16_f32 v109, v118, v119
	global_store_dwordx4 v[114:115], v[106:109], off
	v_pk_mul_f32 v[104:105], v[104:105], v[116:117] op_sel_hi:[1,0]
	s_nop 0
	v_pk_mul_f32 v[106:107], v[100:101], v[116:117] op_sel_hi:[1,0]
	v_pk_mul_f32 v[100:101], v[98:99], v[116:117] op_sel_hi:[1,0]
	v_cvt_pk_bf16_f32 v98, v102, v103
	v_cvt_pk_bf16_f32 v99, v104, v105
	s_nop 0
	v_cvt_pk_bf16_f32 v100, v100, v101
	v_cvt_pk_bf16_f32 v101, v106, v107
	ds_read_b32 v102, v151 offset:128
	global_store_dwordx4 v[114:115], v[98:101], off offset:256
	s_nop 1
	v_add_u32_e32 v98, 32, v140
	v_ashrrev_i32_e32 v99, 31, v98
	v_lshlrev_b64 v[98:99], 11, v[98:99]
	v_lshl_add_u64 v[98:99], s[78:79], 0, v[98:99]
	s_waitcnt lgkmcnt(0)
	v_mul_f32_e32 v100, 0x3d800000, v102
	v_lshl_add_u64 v[98:99], v[98:99], 0, s[10:11]
	v_lshl_add_u64 v[98:99], v[98:99], 0, v[142:143]
	v_pk_mul_f32 v[96:97], v[96:97], v[100:101] op_sel_hi:[1,0]
	v_pk_mul_f32 v[94:95], v[94:95], v[100:101] op_sel_hi:[1,0]
	v_pk_mul_f32 v[102:103], v[92:93], v[100:101] op_sel_hi:[1,0]
	v_pk_mul_f32 v[92:93], v[90:91], v[100:101] op_sel_hi:[1,0]
	v_cvt_pk_bf16_f32 v90, v94, v95
	v_cvt_pk_bf16_f32 v91, v96, v97
	v_pk_mul_f32 v[86:87], v[86:87], v[100:101] op_sel_hi:[1,0]
	v_cvt_pk_bf16_f32 v92, v92, v93
	v_cvt_pk_bf16_f32 v93, v102, v103
	global_store_dwordx4 v[98:99], v[90:93], off
	v_pk_mul_f32 v[88:89], v[88:89], v[100:101] op_sel_hi:[1,0]
	s_nop 0
	v_pk_mul_f32 v[90:91], v[84:85], v[100:101] op_sel_hi:[1,0]
	v_pk_mul_f32 v[84:85], v[82:83], v[100:101] op_sel_hi:[1,0]
	v_cvt_pk_bf16_f32 v82, v86, v87
	v_cvt_pk_bf16_f32 v83, v88, v89
	s_nop 0
	v_cvt_pk_bf16_f32 v84, v84, v85
	v_cvt_pk_bf16_f32 v85, v90, v91
	ds_read_b32 v86, v151 offset:192
	global_store_dwordx4 v[98:99], v[82:85], off offset:256
	s_nop 1
	v_add_u32_e32 v82, 48, v140
	v_ashrrev_i32_e32 v83, 31, v82
	v_lshlrev_b64 v[82:83], 11, v[82:83]
	v_lshl_add_u64 v[82:83], s[78:79], 0, v[82:83]
	s_waitcnt lgkmcnt(0)
	v_mul_f32_e32 v84, 0x3d800000, v86
	v_lshl_add_u64 v[82:83], v[82:83], 0, s[10:11]
	v_lshl_add_u64 v[82:83], v[82:83], 0, v[142:143]
	v_pk_mul_f32 v[80:81], v[80:81], v[84:85] op_sel_hi:[1,0]
	v_pk_mul_f32 v[78:79], v[78:79], v[84:85] op_sel_hi:[1,0]
	v_pk_mul_f32 v[86:87], v[76:77], v[84:85] op_sel_hi:[1,0]
	v_pk_mul_f32 v[76:77], v[74:75], v[84:85] op_sel_hi:[1,0]
	v_cvt_pk_bf16_f32 v74, v78, v79
	v_cvt_pk_bf16_f32 v75, v80, v81
	v_pk_mul_f32 v[70:71], v[70:71], v[84:85] op_sel_hi:[1,0]
	v_cvt_pk_bf16_f32 v76, v76, v77
	v_cvt_pk_bf16_f32 v77, v86, v87
	global_store_dwordx4 v[82:83], v[74:77], off
	v_pk_mul_f32 v[72:73], v[72:73], v[84:85] op_sel_hi:[1,0]
	s_nop 0
	v_pk_mul_f32 v[74:75], v[68:69], v[84:85] op_sel_hi:[1,0]
	v_pk_mul_f32 v[68:69], v[66:67], v[84:85] op_sel_hi:[1,0]
	v_cvt_pk_bf16_f32 v66, v70, v71
	v_cvt_pk_bf16_f32 v67, v72, v73
	s_nop 0
	v_cvt_pk_bf16_f32 v68, v68, v69
	v_cvt_pk_bf16_f32 v69, v74, v75
	ds_read_b32 v70, v151 offset:512
	global_store_dwordx4 v[82:83], v[66:69], off offset:256
	s_nop 1
	v_add_u32_e32 v66, 0x80, v140
	v_ashrrev_i32_e32 v67, 31, v66
	v_lshlrev_b64 v[66:67], 11, v[66:67]
	v_lshl_add_u64 v[66:67], s[78:79], 0, v[66:67]
	s_waitcnt lgkmcnt(0)
	v_mul_f32_e32 v68, 0x3d800000, v70
	v_lshl_add_u64 v[66:67], v[66:67], 0, s[10:11]
	v_lshl_add_u64 v[66:67], v[66:67], 0, v[142:143]
	v_pk_mul_f32 v[64:65], v[64:65], v[68:69] op_sel_hi:[1,0]
	v_pk_mul_f32 v[62:63], v[62:63], v[68:69] op_sel_hi:[1,0]
	v_pk_mul_f32 v[70:71], v[60:61], v[68:69] op_sel_hi:[1,0]
	v_pk_mul_f32 v[60:61], v[58:59], v[68:69] op_sel_hi:[1,0]
	v_cvt_pk_bf16_f32 v58, v62, v63
	v_cvt_pk_bf16_f32 v59, v64, v65
	v_pk_mul_f32 v[54:55], v[54:55], v[68:69] op_sel_hi:[1,0]
	v_cvt_pk_bf16_f32 v60, v60, v61
	v_cvt_pk_bf16_f32 v61, v70, v71
	global_store_dwordx4 v[66:67], v[58:61], off
	v_pk_mul_f32 v[56:57], v[56:57], v[68:69] op_sel_hi:[1,0]
	s_nop 0
	v_pk_mul_f32 v[58:59], v[52:53], v[68:69] op_sel_hi:[1,0]
	v_pk_mul_f32 v[52:53], v[50:51], v[68:69] op_sel_hi:[1,0]
	v_cvt_pk_bf16_f32 v50, v54, v55
	v_cvt_pk_bf16_f32 v51, v56, v57
	s_nop 0
	v_cvt_pk_bf16_f32 v52, v52, v53
	v_cvt_pk_bf16_f32 v53, v58, v59
	ds_read_b32 v54, v151 offset:576
	global_store_dwordx4 v[66:67], v[50:53], off offset:256
	s_nop 1
	v_add_u32_e32 v50, 0x90, v140
	v_ashrrev_i32_e32 v51, 31, v50
	v_lshlrev_b64 v[50:51], 11, v[50:51]
	v_lshl_add_u64 v[50:51], s[78:79], 0, v[50:51]
	s_waitcnt lgkmcnt(0)
	v_mul_f32_e32 v52, 0x3d800000, v54
	v_lshl_add_u64 v[50:51], v[50:51], 0, s[10:11]
	v_lshl_add_u64 v[50:51], v[50:51], 0, v[142:143]
	v_pk_mul_f32 v[48:49], v[48:49], v[52:53] op_sel_hi:[1,0]
	v_pk_mul_f32 v[46:47], v[46:47], v[52:53] op_sel_hi:[1,0]
	v_pk_mul_f32 v[54:55], v[44:45], v[52:53] op_sel_hi:[1,0]
	v_pk_mul_f32 v[44:45], v[42:43], v[52:53] op_sel_hi:[1,0]
	v_cvt_pk_bf16_f32 v42, v46, v47
	v_cvt_pk_bf16_f32 v43, v48, v49
	v_pk_mul_f32 v[38:39], v[38:39], v[52:53] op_sel_hi:[1,0]
	v_cvt_pk_bf16_f32 v44, v44, v45
	v_cvt_pk_bf16_f32 v45, v54, v55
	global_store_dwordx4 v[50:51], v[42:45], off
	v_pk_mul_f32 v[40:41], v[40:41], v[52:53] op_sel_hi:[1,0]
	s_nop 0
	v_pk_mul_f32 v[42:43], v[36:37], v[52:53] op_sel_hi:[1,0]
	v_pk_mul_f32 v[36:37], v[34:35], v[52:53] op_sel_hi:[1,0]
	v_cvt_pk_bf16_f32 v34, v38, v39
	v_cvt_pk_bf16_f32 v35, v40, v41
	s_nop 0
	v_cvt_pk_bf16_f32 v36, v36, v37
	v_cvt_pk_bf16_f32 v37, v42, v43
	ds_read_b32 v38, v151 offset:640
	global_store_dwordx4 v[50:51], v[34:37], off offset:256
	s_nop 1
	v_add_u32_e32 v34, 0xa0, v140
	v_ashrrev_i32_e32 v35, 31, v34
	v_lshlrev_b64 v[34:35], 11, v[34:35]
	v_lshl_add_u64 v[34:35], s[78:79], 0, v[34:35]
	s_waitcnt lgkmcnt(0)
	v_mul_f32_e32 v36, 0x3d800000, v38
	v_lshl_add_u64 v[34:35], v[34:35], 0, s[10:11]
	v_lshl_add_u64 v[34:35], v[34:35], 0, v[142:143]
	v_pk_mul_f32 v[32:33], v[32:33], v[36:37] op_sel_hi:[1,0]
	v_pk_mul_f32 v[30:31], v[30:31], v[36:37] op_sel_hi:[1,0]
	v_pk_mul_f32 v[38:39], v[28:29], v[36:37] op_sel_hi:[1,0]
	v_pk_mul_f32 v[28:29], v[26:27], v[36:37] op_sel_hi:[1,0]
	v_cvt_pk_bf16_f32 v26, v30, v31
	v_cvt_pk_bf16_f32 v27, v32, v33
	v_pk_mul_f32 v[22:23], v[22:23], v[36:37] op_sel_hi:[1,0]
	v_cvt_pk_bf16_f32 v28, v28, v29
	v_cvt_pk_bf16_f32 v29, v38, v39
	global_store_dwordx4 v[34:35], v[26:29], off
	v_pk_mul_f32 v[24:25], v[24:25], v[36:37] op_sel_hi:[1,0]
	s_nop 0
	v_pk_mul_f32 v[26:27], v[20:21], v[36:37] op_sel_hi:[1,0]
	v_pk_mul_f32 v[20:21], v[18:19], v[36:37] op_sel_hi:[1,0]
	v_cvt_pk_bf16_f32 v18, v22, v23
	v_cvt_pk_bf16_f32 v19, v24, v25
	s_nop 0
	v_cvt_pk_bf16_f32 v20, v20, v21
	v_cvt_pk_bf16_f32 v21, v26, v27
	ds_read_b32 v22, v151 offset:704
	global_store_dwordx4 v[34:35], v[18:21], off offset:256
	s_nop 1
	v_add_u32_e32 v18, 0xb0, v140
	v_ashrrev_i32_e32 v19, 31, v18
	v_lshlrev_b64 v[18:19], 11, v[18:19]
	v_lshl_add_u64 v[18:19], s[78:79], 0, v[18:19]
	s_waitcnt lgkmcnt(0)
	v_mul_f32_e32 v20, 0x3d800000, v22
	v_lshl_add_u64 v[18:19], v[18:19], 0, s[10:11]
	v_lshl_add_u64 v[18:19], v[18:19], 0, v[142:143]
	v_pk_mul_f32 v[16:17], v[16:17], v[20:21] op_sel_hi:[1,0]
	v_pk_mul_f32 v[14:15], v[14:15], v[20:21] op_sel_hi:[1,0]
	v_pk_mul_f32 v[22:23], v[12:13], v[20:21] op_sel_hi:[1,0]
	v_pk_mul_f32 v[12:13], v[10:11], v[20:21] op_sel_hi:[1,0]
	v_cvt_pk_bf16_f32 v10, v14, v15
	v_cvt_pk_bf16_f32 v11, v16, v17
	v_pk_mul_f32 v[8:9], v[8:9], v[20:21] op_sel_hi:[1,0]
	v_cvt_pk_bf16_f32 v12, v12, v13
	v_cvt_pk_bf16_f32 v13, v22, v23
	global_store_dwordx4 v[18:19], v[10:13], off
	v_pk_mul_f32 v[6:7], v[6:7], v[20:21] op_sel_hi:[1,0]
	s_nop 0
	v_pk_mul_f32 v[10:11], v[4:5], v[20:21] op_sel_hi:[1,0]
	v_pk_mul_f32 v[4:5], v[2:3], v[20:21] op_sel_hi:[1,0]
	v_cvt_pk_bf16_f32 v2, v6, v7
	v_cvt_pk_bf16_f32 v3, v8, v9
	s_nop 0
	v_cvt_pk_bf16_f32 v4, v4, v5
	v_cvt_pk_bf16_f32 v5, v10, v11
	global_store_dwordx4 v[18:19], v[2:5], off offset:256
	s_and_saveexec_b64 s[10:11], s[12:13]
	s_cbranch_execz .LBB11_1876
	s_waitcnt vmcnt(16)
	v_fmamk_f32 v150, v150, 0x3a800000, v206
	v_mul_f32_e32 v2, 0x4b800000, v150
	v_cmp_gt_f32_e32 vcc, s77, v150
	s_nop 1
	v_cndmask_b32_e32 v2, v150, v2, vcc
	v_rsq_f32_e32 v2, v2
	s_nop 0
	v_mul_f32_e32 v3, 0x45800000, v2
	v_cndmask_b32_e32 v2, v2, v3, vcc
	v_lshl_add_u32 v3, s39, 10, v148
	ds_write_b32 v3, v2

.LBB11_2554:
	s_mul_i32 s6, s50, 0xb00000
	v_readlane_b32 s7, v243, 10
	s_mul_hi_u32 s1, s50, 0xb00000
	s_add_u32 s14, s7, s6
	v_readlane_b32 s6, v243, 11
	s_addc_u32 s15, s6, s1
	s_lshl_b32 s34, s44, 2
	s_or_b32 s0, s0, s34
	s_mul_i32 s0, s0, 0x10400
	v_readlane_b32 s1, v246, 61
	s_add_u32 s16, s1, s0
	v_readlane_b32 s0, v246, 62
	s_addc_u32 s17, s0, 0
	v_readlane_b32 s0, v243, 12
	v_mov_b32_e32 v140, v199
	v_readlane_b32 s1, v243, 13
	s_andn2_b64 vcc, exec, s[0:1]
	v_readfirstlane_b32 s6, v140
	s_cbranch_vccnz .LBB11_2578
	s_movk_i32 s0, 0x100
	v_cmp_gt_i32_e64 s[10:11], s0, v140
	v_readlane_b32 s0, v243, 53
	v_readlane_b32 s1, v243, 54
	s_and_b64 s[0:1], s[10:11], s[0:1]
	v_mov_b32_e32 v250, 1.0
	s_and_saveexec_b64 s[12:13], s[0:1]
	v_readlane_b32 s26, v243, 57
	v_readlane_b32 s27, v243, 58
	s_cbranch_execz .LBB11_2557
	v_readlane_b32 s0, v243, 56
	s_nop 1
	v_add_u32_e32 v2, s0, v140
	v_ashrrev_i32_e32 v3, 31, v2
	v_lshl_add_u64 v[2:3], v[2:3], 2, s[16:17]
	global_load_dword v250, v[2:3], off

.LBB11_2559:
	v_lshl_add_u64 v[10:11], s[28:29], 0, v[0:1]
	v_mov_b32_e32 v135, v1
	v_lshl_add_u64 v[12:13], s[28:29], 0, v[134:135]
	v_mov_b32_e32 v131, v1
	s_add_i32 m0, s36, 0x18000
	v_lshl_add_u64 v[10:11], v[10:11], 0, s[96:97]
	v_lshl_add_u64 v[14:15], s[26:27], 0, v[130:131]
	v_mov_b32_e32 v133, v1
	s_waitcnt vmcnt(2)
	s_barrier
	global_load_lds_dwordx4 v[10:11], off
	v_lshl_add_u64 v[10:11], v[12:13], 0, s[96:97]
	s_add_i32 m0, s36, 0x1a000
	s_add_i32 s40, s36, 0x8000
	s_add_i32 s41, s36, 0xa000
	v_lshl_add_u64 v[16:17], s[26:27], 0, v[132:133]
	global_load_lds_dwordx4 v[10:11], off
	v_lshl_add_u64 v[10:11], v[14:15], 0, s[96:97]
	s_mov_b32 m0, s40
	s_add_u32 s8, s28, 0x40080
	global_load_lds_dwordx4 v[10:11], off
	v_lshl_add_u64 v[10:11], v[16:17], 0, s[96:97]
	s_mov_b32 m0, s41
	s_addc_u32 s9, s29, 0
	global_load_lds_dwordx4 v[10:11], off
	s_add_i32 m0, s36, 0x1c000
	v_lshl_add_u64 v[10:11], s[8:9], 0, v[0:1]
	global_load_lds_dwordx4 v[10:11], off
	v_lshl_add_u64 v[10:11], s[8:9], 0, v[134:135]
	s_add_i32 m0, s36, 0x1e000
	s_nop 0
	global_load_lds_dwordx4 v[10:11], off
	s_waitcnt vmcnt(6)
	s_barrier
	s_and_saveexec_b64 s[12:13], s[10:11]
	s_cbranch_execz .LBB11_2561
	v_fmamk_f32 v3, v250, 0x3a800000, v206
	v_mul_f32_e32 v9, 0x4b800000, v3
	v_cmp_gt_f32_e32 vcc, s77, v3
	s_nop 1
	v_cndmask_b32_e32 v3, v3, v9, vcc
	v_rsq_f32_e32 v3, v3
	v_lshl_add_u32 v9, v140, 2, 0
	v_add_u32_e32 v9, 0x22000, v9
	v_mul_f32_e32 v10, 0x45800000, v3
	v_cndmask_b32_e32 v3, v3, v10, vcc
	ds_write_b32 v9, v3

.LBB11_2570:
	s_cmp_gt_i32 s8, -1
	s_cselect_b64 s[0:1], -1, 0
	s_and_b64 s[0:1], s[10:11], s[0:1]
	v_mov_b32_e32 v146, 1.0
	s_and_saveexec_b64 s[26:27], s[0:1]
	s_cbranch_execz .LBB11_2572
	v_lshl_add_u32 v146, s8, 8, v140
	v_ashrrev_i32_e32 v147, 31, v146
	v_lshl_add_u64 v[146:147], v[146:147], 2, s[16:17]
	global_load_dword v146, v[146:147], off
.LBB11_2572:
	s_or_b64 exec, exec, s[26:27]
	s_lshl_b32 s0, s42, 10
	v_mov_b32_e32 v148, v143
	v_mov_b32_e32 v149, v141
	s_add_i32 s0, s0, 0
	s_xor_b32 s42, s42, 1
	v_lshl_add_u32 v147, v149, 2, s0
	v_add_u32_e32 v147, 0x22000, v147
	ds_read_b32 v150, v147
	s_movk_i32 s0, 0xb00
	s_waitcnt lgkmcnt(0)
	v_mul_f32_e32 v152, 0xbfb8aa3b, v150
	v_pk_mul_f32 v[154:155], v[126:127], v[152:153] op_sel_hi:[1,0]
	v_pk_mul_f32 v[126:127], v[126:127], v[150:151] op_sel_hi:[1,0]
	v_pk_mul_f32 v[122:123], v[122:123], v[150:151] op_sel_hi:[1,0]
	v_pk_mul_f32 v[124:125], v[124:125], v[150:151] op_sel_hi:[1,0]
	v_pk_mul_f32 v[122:123], v[126:127], v[122:123]
	v_pk_mul_f32 v[126:127], v[128:129], v[152:153] op_sel_hi:[1,0]
	v_pk_mul_f32 v[128:129], v[128:129], v[150:151] op_sel_hi:[1,0]
	v_exp_f32_e32 v126, v126
	v_exp_f32_e32 v127, v127
	v_pk_mul_f32 v[124:125], v[128:129], v[124:125]
	v_pk_mul_f32 v[114:115], v[114:115], v[150:151] op_sel_hi:[1,0]
	v_exp_f32_e32 v154, v154
	v_pk_add_f32 v[126:127], v[126:127], 1.0 op_sel_hi:[1,0]
	v_exp_f32_e32 v155, v155
	v_rcp_f32_e32 v126, v126
	v_rcp_f32_e32 v127, v127
	v_pk_mul_f32 v[116:117], v[116:117], v[150:151] op_sel_hi:[1,0]
	v_pk_add_f32 v[154:155], v[154:155], 1.0 op_sel_hi:[1,0]
	v_pk_mul_f32 v[124:125], v[124:125], v[126:127]
	v_pk_mul_f32 v[126:127], v[118:119], v[152:153] op_sel_hi:[1,0]
	v_pk_mul_f32 v[118:119], v[118:119], v[150:151] op_sel_hi:[1,0]
	v_exp_f32_e32 v126, v126
	v_exp_f32_e32 v127, v127
	v_pk_mul_f32 v[114:115], v[118:119], v[114:115]
	v_pk_mul_f32 v[118:119], v[120:121], v[152:153] op_sel_hi:[1,0]
	v_rcp_f32_e32 v154, v154
	v_exp_f32_e32 v118, v118
	v_exp_f32_e32 v119, v119
	v_pk_add_f32 v[126:127], v[126:127], 1.0 op_sel_hi:[1,0]
	v_rcp_f32_e32 v155, v155
	v_rcp_f32_e32 v126, v126
	v_rcp_f32_e32 v127, v127
	v_pk_add_f32 v[118:119], v[118:119], 1.0 op_sel_hi:[1,0]
	v_pk_mul_f32 v[120:121], v[120:121], v[150:151] op_sel_hi:[1,0]
	v_rcp_f32_e32 v118, v118
	v_rcp_f32_e32 v119, v119
	v_pk_mul_f32 v[114:115], v[114:115], v[126:127]
	v_pk_mul_f32 v[116:117], v[120:121], v[116:117]
	v_lshl_add_u32 v126, s7, 8, v149
	v_pk_mul_f32 v[122:123], v[122:123], v[154:155]
	v_pk_mul_f32 v[120:121], v[116:117], v[118:119]
	v_cvt_pk_bf16_f32 v116, v122, v123
	v_cvt_pk_bf16_f32 v117, v124, v125
	v_cvt_pk_bf16_f32 v118, v114, v115
	v_mad_u64_u32 v[114:115], s[0:1], v126, s0, v[148:149]
	s_lshl_b32 s0, s6, 8
	s_nop 0
	v_lshl_add_u32 v114, v114, 1, s0
	v_cvt_pk_bf16_f32 v119, v120, v121
	buffer_store_dwordx4 v[116:119], v114, s[52:55], 0 offen sc1
	ds_read_b32 v116, v147 offset:64
	s_waitcnt lgkmcnt(0)
	v_pk_mul_f32 v[106:107], v[106:107], v[116:117] op_sel_hi:[1,0]
	v_mul_f32_e32 v118, 0xbfb8aa3b, v116
	v_pk_mul_f32 v[120:121], v[110:111], v[118:119] op_sel_hi:[1,0]
	v_pk_mul_f32 v[110:111], v[110:111], v[116:117] op_sel_hi:[1,0]
	v_pk_mul_f32 v[108:109], v[108:109], v[116:117] op_sel_hi:[1,0]
	v_pk_mul_f32 v[106:107], v[110:111], v[106:107]
	v_pk_mul_f32 v[110:111], v[112:113], v[118:119] op_sel_hi:[1,0]
	v_pk_mul_f32 v[112:113], v[112:113], v[116:117] op_sel_hi:[1,0]
	v_exp_f32_e32 v110, v110
	v_exp_f32_e32 v111, v111
	v_pk_mul_f32 v[108:109], v[112:113], v[108:109]
	v_pk_mul_f32 v[98:99], v[98:99], v[116:117] op_sel_hi:[1,0]
	v_exp_f32_e32 v120, v120
	v_pk_add_f32 v[110:111], v[110:111], 1.0 op_sel_hi:[1,0]
	v_exp_f32_e32 v121, v121
	v_rcp_f32_e32 v110, v110
	v_rcp_f32_e32 v111, v111
	v_pk_mul_f32 v[100:101], v[100:101], v[116:117] op_sel_hi:[1,0]
	v_pk_add_f32 v[120:121], v[120:121], 1.0 op_sel_hi:[1,0]
	v_pk_mul_f32 v[108:109], v[108:109], v[110:111]
	v_pk_mul_f32 v[110:111], v[102:103], v[118:119] op_sel_hi:[1,0]
	v_pk_mul_f32 v[102:103], v[102:103], v[116:117] op_sel_hi:[1,0]
	v_exp_f32_e32 v110, v110
	v_exp_f32_e32 v111, v111
	v_pk_mul_f32 v[98:99], v[102:103], v[98:99]
	v_rcp_f32_e32 v120, v120
	v_rcp_f32_e32 v121, v121
	v_pk_add_f32 v[110:111], v[110:111], 1.0 op_sel_hi:[1,0]
	v_pk_mul_f32 v[106:107], v[106:107], v[120:121]
	v_rcp_f32_e32 v110, v110
	v_rcp_f32_e32 v111, v111
	s_nop 0
	v_pk_mul_f32 v[102:103], v[98:99], v[110:111]
	v_pk_mul_f32 v[98:99], v[104:105], v[118:119] op_sel_hi:[1,0]
	v_pk_mul_f32 v[104:105], v[104:105], v[116:117] op_sel_hi:[1,0]
	v_exp_f32_e32 v98, v98
	v_exp_f32_e32 v99, v99
	v_pk_mul_f32 v[100:101], v[104:105], v[100:101]
	v_pk_add_f32 v[98:99], v[98:99], 1.0 op_sel_hi:[1,0]
	s_nop 0
	v_rcp_f32_e32 v98, v98
	v_rcp_f32_e32 v99, v99
	s_nop 0
	v_pk_mul_f32 v[104:105], v[100:101], v[98:99]
	v_cvt_pk_bf16_f32 v98, v106, v107
	v_cvt_pk_bf16_f32 v99, v108, v109
	v_cvt_pk_bf16_f32 v100, v102, v103
	v_add_u32_e32 v102, 0x16000, v114
	v_cvt_pk_bf16_f32 v101, v104, v105
	buffer_store_dwordx4 v[98:101], v102, s[52:55], 0 offen sc1
	ds_read_b32 v98, v147 offset:128
	s_waitcnt lgkmcnt(0)
	v_pk_mul_f32 v[90:91], v[90:91], v[98:99] op_sel_hi:[1,0]
	v_mul_f32_e32 v100, 0xbfb8aa3b, v98
	v_pk_mul_f32 v[102:103], v[94:95], v[100:101] op_sel_hi:[1,0]
	v_pk_mul_f32 v[94:95], v[94:95], v[98:99] op_sel_hi:[1,0]
	v_pk_mul_f32 v[92:93], v[92:93], v[98:99] op_sel_hi:[1,0]
	v_pk_mul_f32 v[90:91], v[94:95], v[90:91]
	v_pk_mul_f32 v[94:95], v[96:97], v[100:101] op_sel_hi:[1,0]
	v_pk_mul_f32 v[96:97], v[96:97], v[98:99] op_sel_hi:[1,0]
	v_exp_f32_e32 v94, v94
	v_exp_f32_e32 v95, v95
	v_pk_mul_f32 v[92:93], v[96:97], v[92:93]
	v_pk_mul_f32 v[82:83], v[82:83], v[98:99] op_sel_hi:[1,0]
	v_exp_f32_e32 v102, v102
	v_pk_add_f32 v[94:95], v[94:95], 1.0 op_sel_hi:[1,0]
	v_exp_f32_e32 v103, v103
	v_rcp_f32_e32 v94, v94
	v_rcp_f32_e32 v95, v95
	v_pk_mul_f32 v[84:85], v[84:85], v[98:99] op_sel_hi:[1,0]
	v_pk_add_f32 v[102:103], v[102:103], 1.0 op_sel_hi:[1,0]
	v_pk_mul_f32 v[92:93], v[92:93], v[94:95]
	v_pk_mul_f32 v[94:95], v[86:87], v[100:101] op_sel_hi:[1,0]
	v_pk_mul_f32 v[86:87], v[86:87], v[98:99] op_sel_hi:[1,0]
	v_exp_f32_e32 v94, v94
	v_exp_f32_e32 v95, v95
	v_pk_mul_f32 v[82:83], v[86:87], v[82:83]
	v_rcp_f32_e32 v102, v102
	v_rcp_f32_e32 v103, v103
	v_pk_add_f32 v[94:95], v[94:95], 1.0 op_sel_hi:[1,0]
	v_pk_mul_f32 v[90:91], v[90:91], v[102:103]
	v_rcp_f32_e32 v94, v94
	v_rcp_f32_e32 v95, v95
	s_nop 0
	v_pk_mul_f32 v[86:87], v[82:83], v[94:95]
	v_pk_mul_f32 v[82:83], v[88:89], v[100:101] op_sel_hi:[1,0]
	v_pk_mul_f32 v[88:89], v[88:89], v[98:99] op_sel_hi:[1,0]
	v_exp_f32_e32 v82, v82
	v_exp_f32_e32 v83, v83
	v_pk_mul_f32 v[84:85], v[88:89], v[84:85]
	v_pk_add_f32 v[82:83], v[82:83], 1.0 op_sel_hi:[1,0]
	s_nop 0
	v_rcp_f32_e32 v82, v82
	v_rcp_f32_e32 v83, v83
	s_nop 0
	v_pk_mul_f32 v[88:89], v[84:85], v[82:83]
	v_cvt_pk_bf16_f32 v82, v90, v91
	v_cvt_pk_bf16_f32 v83, v92, v93
	v_cvt_pk_bf16_f32 v84, v86, v87
	v_add_u32_e32 v86, 0x2c000, v114
	v_cvt_pk_bf16_f32 v85, v88, v89
	buffer_store_dwordx4 v[82:85], v86, s[52:55], 0 offen sc1
	ds_read_b32 v82, v147 offset:192
	s_waitcnt lgkmcnt(0)
	v_pk_mul_f32 v[74:75], v[74:75], v[82:83] op_sel_hi:[1,0]
	v_mul_f32_e32 v84, 0xbfb8aa3b, v82
	v_pk_mul_f32 v[86:87], v[78:79], v[84:85] op_sel_hi:[1,0]
	v_pk_mul_f32 v[78:79], v[78:79], v[82:83] op_sel_hi:[1,0]
	v_pk_mul_f32 v[76:77], v[76:77], v[82:83] op_sel_hi:[1,0]
	v_pk_mul_f32 v[74:75], v[78:79], v[74:75]
	v_pk_mul_f32 v[78:79], v[80:81], v[84:85] op_sel_hi:[1,0]
	v_pk_mul_f32 v[80:81], v[80:81], v[82:83] op_sel_hi:[1,0]
	v_exp_f32_e32 v78, v78
	v_exp_f32_e32 v79, v79
	v_pk_mul_f32 v[76:77], v[80:81], v[76:77]
	v_pk_mul_f32 v[66:67], v[66:67], v[82:83] op_sel_hi:[1,0]
	v_exp_f32_e32 v86, v86
	v_pk_add_f32 v[78:79], v[78:79], 1.0 op_sel_hi:[1,0]
	v_exp_f32_e32 v87, v87
	v_rcp_f32_e32 v78, v78
	v_rcp_f32_e32 v79, v79
	v_pk_mul_f32 v[68:69], v[68:69], v[82:83] op_sel_hi:[1,0]
	v_pk_add_f32 v[86:87], v[86:87], 1.0 op_sel_hi:[1,0]
	v_pk_mul_f32 v[76:77], v[76:77], v[78:79]
	v_pk_mul_f32 v[78:79], v[70:71], v[84:85] op_sel_hi:[1,0]
	v_pk_mul_f32 v[70:71], v[70:71], v[82:83] op_sel_hi:[1,0]
	v_exp_f32_e32 v78, v78
	v_exp_f32_e32 v79, v79
	v_pk_mul_f32 v[66:67], v[70:71], v[66:67]
	v_rcp_f32_e32 v86, v86
	v_rcp_f32_e32 v87, v87
	v_pk_add_f32 v[78:79], v[78:79], 1.0 op_sel_hi:[1,0]
	v_pk_mul_f32 v[74:75], v[74:75], v[86:87]
	v_rcp_f32_e32 v78, v78
	v_rcp_f32_e32 v79, v79
	s_nop 0
	v_pk_mul_f32 v[70:71], v[66:67], v[78:79]
	v_pk_mul_f32 v[66:67], v[72:73], v[84:85] op_sel_hi:[1,0]
	v_pk_mul_f32 v[72:73], v[72:73], v[82:83] op_sel_hi:[1,0]
	v_exp_f32_e32 v66, v66
	v_exp_f32_e32 v67, v67
	v_pk_mul_f32 v[68:69], v[72:73], v[68:69]
	v_pk_add_f32 v[66:67], v[66:67], 1.0 op_sel_hi:[1,0]
	s_nop 0
	v_rcp_f32_e32 v66, v66
	v_rcp_f32_e32 v67, v67
	s_nop 0
	v_pk_mul_f32 v[72:73], v[68:69], v[66:67]
	v_cvt_pk_bf16_f32 v66, v74, v75
	v_cvt_pk_bf16_f32 v67, v76, v77
	v_cvt_pk_bf16_f32 v68, v70, v71
	v_add_u32_e32 v70, 0x42000, v114
	v_cvt_pk_bf16_f32 v69, v72, v73
	buffer_store_dwordx4 v[66:69], v70, s[52:55], 0 offen sc1
	ds_read_b32 v66, v147 offset:512
	s_waitcnt lgkmcnt(0)
	v_pk_mul_f32 v[58:59], v[58:59], v[66:67] op_sel_hi:[1,0]
	v_mul_f32_e32 v68, 0xbfb8aa3b, v66
	v_pk_mul_f32 v[70:71], v[62:63], v[68:69] op_sel_hi:[1,0]
	v_pk_mul_f32 v[62:63], v[62:63], v[66:67] op_sel_hi:[1,0]
	v_pk_mul_f32 v[60:61], v[60:61], v[66:67] op_sel_hi:[1,0]
	v_pk_mul_f32 v[58:59], v[62:63], v[58:59]
	v_pk_mul_f32 v[62:63], v[64:65], v[68:69] op_sel_hi:[1,0]
	v_pk_mul_f32 v[64:65], v[64:65], v[66:67] op_sel_hi:[1,0]
	v_exp_f32_e32 v62, v62
	v_exp_f32_e32 v63, v63
	v_pk_mul_f32 v[60:61], v[64:65], v[60:61]
	v_pk_mul_f32 v[50:51], v[50:51], v[66:67] op_sel_hi:[1,0]
	v_exp_f32_e32 v70, v70
	v_pk_add_f32 v[62:63], v[62:63], 1.0 op_sel_hi:[1,0]
	v_exp_f32_e32 v71, v71
	v_rcp_f32_e32 v62, v62
	v_rcp_f32_e32 v63, v63
	v_pk_mul_f32 v[52:53], v[52:53], v[66:67] op_sel_hi:[1,0]
	v_pk_add_f32 v[70:71], v[70:71], 1.0 op_sel_hi:[1,0]
	v_pk_mul_f32 v[60:61], v[60:61], v[62:63]
	v_pk_mul_f32 v[62:63], v[54:55], v[68:69] op_sel_hi:[1,0]
	v_pk_mul_f32 v[54:55], v[54:55], v[66:67] op_sel_hi:[1,0]
	v_exp_f32_e32 v62, v62
	v_exp_f32_e32 v63, v63
	v_pk_mul_f32 v[50:51], v[54:55], v[50:51]
	v_rcp_f32_e32 v70, v70
	v_rcp_f32_e32 v71, v71
	v_pk_add_f32 v[62:63], v[62:63], 1.0 op_sel_hi:[1,0]
	v_pk_mul_f32 v[58:59], v[58:59], v[70:71]
	v_rcp_f32_e32 v62, v62
	v_rcp_f32_e32 v63, v63
	s_nop 0
	v_pk_mul_f32 v[54:55], v[50:51], v[62:63]
	v_pk_mul_f32 v[50:51], v[56:57], v[68:69] op_sel_hi:[1,0]
	v_pk_mul_f32 v[56:57], v[56:57], v[66:67] op_sel_hi:[1,0]
	v_exp_f32_e32 v50, v50
	v_exp_f32_e32 v51, v51
	v_pk_mul_f32 v[52:53], v[56:57], v[52:53]
	v_pk_add_f32 v[50:51], v[50:51], 1.0 op_sel_hi:[1,0]
	s_nop 0
	v_rcp_f32_e32 v50, v50
	v_rcp_f32_e32 v51, v51
	s_nop 0
	v_pk_mul_f32 v[56:57], v[52:53], v[50:51]
	v_cvt_pk_bf16_f32 v50, v58, v59
	v_cvt_pk_bf16_f32 v51, v60, v61
	v_cvt_pk_bf16_f32 v52, v54, v55
	v_add_u32_e32 v54, 0xb0000, v114
	v_cvt_pk_bf16_f32 v53, v56, v57
	buffer_store_dwordx4 v[50:53], v54, s[52:55], 0 offen sc1
	ds_read_b32 v50, v147 offset:576
	s_waitcnt lgkmcnt(0)
	v_pk_mul_f32 v[42:43], v[42:43], v[50:51] op_sel_hi:[1,0]
	v_mul_f32_e32 v52, 0xbfb8aa3b, v50
	v_pk_mul_f32 v[54:55], v[46:47], v[52:53] op_sel_hi:[1,0]
	v_pk_mul_f32 v[46:47], v[46:47], v[50:51] op_sel_hi:[1,0]
	v_pk_mul_f32 v[44:45], v[44:45], v[50:51] op_sel_hi:[1,0]
	v_pk_mul_f32 v[42:43], v[46:47], v[42:43]
	v_pk_mul_f32 v[46:47], v[48:49], v[52:53] op_sel_hi:[1,0]
	v_pk_mul_f32 v[48:49], v[48:49], v[50:51] op_sel_hi:[1,0]
	v_exp_f32_e32 v46, v46
	v_exp_f32_e32 v47, v47
	v_pk_mul_f32 v[44:45], v[48:49], v[44:45]
	v_pk_mul_f32 v[34:35], v[34:35], v[50:51] op_sel_hi:[1,0]
	v_exp_f32_e32 v54, v54
	v_pk_add_f32 v[46:47], v[46:47], 1.0 op_sel_hi:[1,0]
	v_exp_f32_e32 v55, v55
	v_rcp_f32_e32 v46, v46
	v_rcp_f32_e32 v47, v47
	v_pk_mul_f32 v[36:37], v[36:37], v[50:51] op_sel_hi:[1,0]
	v_pk_add_f32 v[54:55], v[54:55], 1.0 op_sel_hi:[1,0]
	v_pk_mul_f32 v[44:45], v[44:45], v[46:47]
	v_pk_mul_f32 v[46:47], v[38:39], v[52:53] op_sel_hi:[1,0]
	v_pk_mul_f32 v[38:39], v[38:39], v[50:51] op_sel_hi:[1,0]
	v_exp_f32_e32 v46, v46
	v_exp_f32_e32 v47, v47
	v_pk_mul_f32 v[34:35], v[38:39], v[34:35]
	v_rcp_f32_e32 v54, v54
	v_rcp_f32_e32 v55, v55
	v_pk_add_f32 v[46:47], v[46:47], 1.0 op_sel_hi:[1,0]
	v_pk_mul_f32 v[42:43], v[42:43], v[54:55]
	v_rcp_f32_e32 v46, v46
	v_rcp_f32_e32 v47, v47
	s_nop 0
	v_pk_mul_f32 v[38:39], v[34:35], v[46:47]
	v_pk_mul_f32 v[34:35], v[40:41], v[52:53] op_sel_hi:[1,0]
	v_pk_mul_f32 v[40:41], v[40:41], v[50:51] op_sel_hi:[1,0]
	v_exp_f32_e32 v34, v34
	v_exp_f32_e32 v35, v35
	v_pk_mul_f32 v[36:37], v[40:41], v[36:37]
	v_pk_add_f32 v[34:35], v[34:35], 1.0 op_sel_hi:[1,0]
	s_nop 0
	v_rcp_f32_e32 v34, v34
	v_rcp_f32_e32 v35, v35
	s_nop 0
	v_pk_mul_f32 v[40:41], v[36:37], v[34:35]
	v_cvt_pk_bf16_f32 v34, v42, v43
	v_cvt_pk_bf16_f32 v35, v44, v45
	v_cvt_pk_bf16_f32 v36, v38, v39
	v_add_u32_e32 v38, 0xc6000, v114
	v_cvt_pk_bf16_f32 v37, v40, v41
	buffer_store_dwordx4 v[34:37], v38, s[52:55], 0 offen sc1
	ds_read_b32 v34, v147 offset:640
	s_waitcnt lgkmcnt(0)
	v_pk_mul_f32 v[26:27], v[26:27], v[34:35] op_sel_hi:[1,0]
	v_mul_f32_e32 v36, 0xbfb8aa3b, v34
	v_pk_mul_f32 v[38:39], v[30:31], v[36:37] op_sel_hi:[1,0]
	v_pk_mul_f32 v[30:31], v[30:31], v[34:35] op_sel_hi:[1,0]
	v_pk_mul_f32 v[28:29], v[28:29], v[34:35] op_sel_hi:[1,0]
	v_pk_mul_f32 v[26:27], v[30:31], v[26:27]
	v_pk_mul_f32 v[30:31], v[32:33], v[36:37] op_sel_hi:[1,0]
	v_pk_mul_f32 v[32:33], v[32:33], v[34:35] op_sel_hi:[1,0]
	v_exp_f32_e32 v30, v30
	v_exp_f32_e32 v31, v31
	v_pk_mul_f32 v[28:29], v[32:33], v[28:29]
	v_pk_mul_f32 v[18:19], v[18:19], v[34:35] op_sel_hi:[1,0]
	v_exp_f32_e32 v38, v38
	v_pk_add_f32 v[30:31], v[30:31], 1.0 op_sel_hi:[1,0]
	v_exp_f32_e32 v39, v39
	v_rcp_f32_e32 v30, v30
	v_rcp_f32_e32 v31, v31
	v_pk_mul_f32 v[20:21], v[20:21], v[34:35] op_sel_hi:[1,0]
	v_pk_add_f32 v[38:39], v[38:39], 1.0 op_sel_hi:[1,0]
	v_pk_mul_f32 v[28:29], v[28:29], v[30:31]
	v_pk_mul_f32 v[30:31], v[22:23], v[36:37] op_sel_hi:[1,0]
	v_pk_mul_f32 v[22:23], v[22:23], v[34:35] op_sel_hi:[1,0]
	v_exp_f32_e32 v30, v30
	v_exp_f32_e32 v31, v31
	v_pk_mul_f32 v[18:19], v[22:23], v[18:19]
	v_rcp_f32_e32 v38, v38
	v_rcp_f32_e32 v39, v39
	v_pk_add_f32 v[30:31], v[30:31], 1.0 op_sel_hi:[1,0]
	v_pk_mul_f32 v[26:27], v[26:27], v[38:39]
	v_rcp_f32_e32 v30, v30
	v_rcp_f32_e32 v31, v31
	s_nop 0
	v_pk_mul_f32 v[22:23], v[18:19], v[30:31]
	v_pk_mul_f32 v[18:19], v[24:25], v[36:37] op_sel_hi:[1,0]
	v_pk_mul_f32 v[24:25], v[24:25], v[34:35] op_sel_hi:[1,0]
	v_exp_f32_e32 v18, v18
	v_exp_f32_e32 v19, v19
	v_pk_mul_f32 v[20:21], v[24:25], v[20:21]
	v_pk_add_f32 v[18:19], v[18:19], 1.0 op_sel_hi:[1,0]
	s_nop 0
	v_rcp_f32_e32 v18, v18
	v_rcp_f32_e32 v19, v19
	s_nop 0
	v_pk_mul_f32 v[24:25], v[20:21], v[18:19]
	v_cvt_pk_bf16_f32 v18, v26, v27
	v_cvt_pk_bf16_f32 v19, v28, v29
	v_cvt_pk_bf16_f32 v20, v22, v23
	v_add_u32_e32 v22, 0xdc000, v114
	v_cvt_pk_bf16_f32 v21, v24, v25
	buffer_store_dwordx4 v[18:21], v22, s[52:55], 0 offen sc1
	ds_read_b32 v18, v147 offset:704
	s_waitcnt lgkmcnt(0)
	v_pk_mul_f32 v[10:11], v[10:11], v[18:19] op_sel_hi:[1,0]
	v_mul_f32_e32 v20, 0xbfb8aa3b, v18
	v_pk_mul_f32 v[22:23], v[14:15], v[20:21] op_sel_hi:[1,0]
	v_pk_mul_f32 v[14:15], v[14:15], v[18:19] op_sel_hi:[1,0]
	v_pk_mul_f32 v[12:13], v[12:13], v[18:19] op_sel_hi:[1,0]
	v_pk_mul_f32 v[10:11], v[14:15], v[10:11]
	v_pk_mul_f32 v[14:15], v[16:17], v[20:21] op_sel_hi:[1,0]
	v_pk_mul_f32 v[16:17], v[16:17], v[18:19] op_sel_hi:[1,0]
	v_exp_f32_e32 v14, v14
	v_exp_f32_e32 v15, v15
	v_pk_mul_f32 v[12:13], v[16:17], v[12:13]
	v_pk_mul_f32 v[2:3], v[2:3], v[18:19] op_sel_hi:[1,0]
	v_exp_f32_e32 v22, v22
	v_pk_add_f32 v[14:15], v[14:15], 1.0 op_sel_hi:[1,0]
	v_exp_f32_e32 v23, v23
	v_rcp_f32_e32 v14, v14
	v_rcp_f32_e32 v15, v15
	v_pk_mul_f32 v[4:5], v[4:5], v[18:19] op_sel_hi:[1,0]
	v_pk_add_f32 v[22:23], v[22:23], 1.0 op_sel_hi:[1,0]
	v_pk_mul_f32 v[12:13], v[12:13], v[14:15]
	v_pk_mul_f32 v[14:15], v[6:7], v[20:21] op_sel_hi:[1,0]
	v_pk_mul_f32 v[6:7], v[6:7], v[18:19] op_sel_hi:[1,0]
	v_exp_f32_e32 v14, v14
	v_exp_f32_e32 v15, v15
	v_pk_mul_f32 v[2:3], v[6:7], v[2:3]
	v_rcp_f32_e32 v22, v22
	v_rcp_f32_e32 v23, v23
	v_pk_add_f32 v[14:15], v[14:15], 1.0 op_sel_hi:[1,0]
	v_pk_mul_f32 v[10:11], v[10:11], v[22:23]
	v_rcp_f32_e32 v14, v14
	v_rcp_f32_e32 v15, v15
	s_nop 0
	v_pk_mul_f32 v[6:7], v[2:3], v[14:15]
	v_pk_mul_f32 v[2:3], v[8:9], v[20:21] op_sel_hi:[1,0]
	v_pk_mul_f32 v[8:9], v[8:9], v[18:19] op_sel_hi:[1,0]
	v_exp_f32_e32 v2, v2
	v_exp_f32_e32 v3, v3
	v_pk_mul_f32 v[4:5], v[8:9], v[4:5]
	v_pk_add_f32 v[2:3], v[2:3], 1.0 op_sel_hi:[1,0]
	s_nop 0
	v_rcp_f32_e32 v2, v2
	v_rcp_f32_e32 v3, v3
	s_nop 0
	v_pk_mul_f32 v[8:9], v[4:5], v[2:3]
	v_cvt_pk_bf16_f32 v2, v10, v11
	v_cvt_pk_bf16_f32 v3, v12, v13
	v_cvt_pk_bf16_f32 v4, v6, v7
	v_add_u32_e32 v6, 0xf2000, v114
	v_cvt_pk_bf16_f32 v5, v8, v9
	buffer_store_dwordx4 v[2:5], v6, s[52:55], 0 offen sc1
	s_and_saveexec_b64 s[26:27], s[10:11]
	s_cbranch_execz .LBB11_2574
	s_waitcnt vmcnt(8)
	v_fmamk_f32 v146, v146, 0x3a800000, v206
	v_mul_f32_e32 v2, 0x4b800000, v146
	v_cmp_gt_f32_e32 vcc, s77, v146
	s_nop 1
	v_cndmask_b32_e32 v2, v146, v2, vcc
	v_rsq_f32_e32 v2, v2
	s_nop 0
	v_mul_f32_e32 v3, 0x45800000, v2
	v_cndmask_b32_e32 v2, v2, v3, vcc
	v_lshl_add_u32 v3, s42, 10, v144
	ds_write_b32 v3, v2
